# EpiRes P5+P7 epilogues: residual loads batched per tile instead of one round trip per 8-column group
# baseline (speedup 1.0000x reference)
; __device__ __forceinline__ u32x4 pack8(f32x4 a, f32x4 b) { u32x4 w; w.x = cvt_pk(a[0], a[1]); w.y = cvt_pk(a[2], a[3]); w.z = cvt_pk(b[0], b[1]); w.w = cvt_pk(b[2], b[3]); return w; }
;     __device__ __forceinline__ void operator()(EPI_ARGS) const {
;         const int row0 = u.pm * 256 + wr * 64 + fr, colt = u.pn * 256 + wc * 32 + 8 * fq;
; #pragma unroll
;         for (int ai = 0; ai < 2; ++ai)
; #pragma unroll
;             for (int m = 0; m < 4; ++m) { const int row = row0 + ai * 128 + m * 16; const size_t ro = (size_t)row * DM + colt; float s = 0.f;
; #pragma unroll
;                 for (int bj = 0; bj < 2; ++bj) { const size_t o = ro + bj * 128;
;                     f32x4 v0 = acc[ai][bj][m][0], v1 = acc[ai][bj][m][1];
;                     if (IN_BF16) { const u32x4 t = *(const u32x4*)((const bf16_t*)xin + o);
;                         v0[0] += bflo(t.x); v0[1] += bfhi(t.x); v0[2] += bflo(t.y); v0[3] += bfhi(t.y); v1[0] += bflo(t.z); v1[1] += bfhi(t.z); v1[2] += bflo(t.w); v1[3] += bfhi(t.w);
;                     } else { v0 = v0 + *(const f32x4*)((const float*)xin + o); v1 = v1 + *(const f32x4*)((const float*)xin + o + 4); }
;                     *(u32x4*)(xb + o) = pack8(v0, v1);
;                     s += ((v0[0] * v0[0] + v0[1] * v0[1]) + (v0[2] * v0[2] + v0[3] * v0[3])) + ((v1[0] * v1[0] + v1[1] * v1[1]) + (v1[2] * v1[2] + v1[3] * v1[3])); }
.LBB0_963:
	s_lshl_b32 s15, s35, 8
	s_or_b32 s15, s15, s43
	v_ashrrev_i32_e32 v140, 1, v144
	v_and_b32_e32 v140, -8, v140
	v_add_u32_e32 v140, s15, v140
	v_and_or_b32 v141, v144, 15, s42
	v_lshl_add_u32 v142, s4, 8, v141
	v_lshlrev_b32_e32 v223, 11, v142
	v_lshl_add_u32 v223, v140, 1, v223
	s_lshl_b32 s15, s35, 4
	s_lshl_b32 s24, s41, 2
	s_add_i32 s15, s15, s24
	v_lshl_add_u32 v224, v142, 6, s15
	v_xor_b32_e32 v225, 16, v144
	v_lshlrev_b32_e32 v225, 2, v225
	v_xor_b32_e32 v226, 32, v144
	v_lshlrev_b32_e32 v226, 2, v226
	v_cmp_gt_u32_e32 vcc, 16, v144
	s_mov_b64 s[98:99], s[72:73]
	s_mov_b64 s[100:101], s[88:89]
	s_mov_b64 s[24:25], s[8:9]
	global_load_dwordx4 v[150:153], v223, s[98:99]
	global_load_dwordx4 v[154:157], v223, s[98:99] offset:256
	s_add_u32 s98, s98, 0x8000
	s_addc_u32 s99, s99, 0
	global_load_dwordx4 v[158:161], v223, s[98:99]
	global_load_dwordx4 v[162:165], v223, s[98:99] offset:256
	s_add_u32 s98, s98, 0x8000
	s_addc_u32 s99, s99, 0
	global_load_dwordx4 v[166:169], v223, s[98:99]
	global_load_dwordx4 v[170:173], v223, s[98:99] offset:256
	s_add_u32 s98, s98, 0x8000
	s_addc_u32 s99, s99, 0
	global_load_dwordx4 v[174:177], v223, s[98:99]
	global_load_dwordx4 v[178:181], v223, s[98:99] offset:256
	s_add_u32 s98, s98, 0x28000
	s_addc_u32 s99, s99, 0
	global_load_dwordx4 v[186:189], v223, s[98:99]
	global_load_dwordx4 v[190:193], v223, s[98:99] offset:256
	s_add_u32 s98, s98, 0x8000
	s_addc_u32 s99, s99, 0
	global_load_dwordx4 v[194:197], v223, s[98:99]
	global_load_dwordx4 v[198:201], v223, s[98:99] offset:256
	s_add_u32 s98, s98, 0x8000
	s_addc_u32 s99, s99, 0
	global_load_dwordx4 v[202:205], v223, s[98:99]
	global_load_dwordx4 v[206:209], v223, s[98:99] offset:256
	s_add_u32 s98, s98, 0x8000
	s_addc_u32 s99, s99, 0
	global_load_dwordx4 v[210:213], v223, s[98:99]
	global_load_dwordx4 v[238:241], v223, s[98:99] offset:256
	s_add_u32 s98, s98, 0x28000
	s_addc_u32 s99, s99, 0
	s_waitcnt vmcnt(0)
	v_lshlrev_b32_e32 v220, 16, v150
	v_and_b32_e32 v221, 0xffff0000, v150
	v_pk_add_f32 v[124:125], v[124:125], v[220:221]
	v_lshlrev_b32_e32 v220, 16, v151
	v_and_b32_e32 v221, 0xffff0000, v151
	v_pk_add_f32 v[126:127], v[126:127], v[220:221]
	v_lshlrev_b32_e32 v220, 16, v152
	v_and_b32_e32 v221, 0xffff0000, v152
	v_pk_add_f32 v[120:121], v[120:121], v[220:221]
	v_lshlrev_b32_e32 v220, 16, v153
	v_and_b32_e32 v221, 0xffff0000, v153
	v_pk_add_f32 v[122:123], v[122:123], v[220:221]
	v_pk_mul_f32 v[242:243], v[124:125], v[124:125]
	v_pk_mul_f32 v[244:245], v[126:127], v[126:127]
	v_pk_mul_f32 v[216:217], v[120:121], v[120:121]
	v_pk_mul_f32 v[218:219], v[122:123], v[122:123]
	v_add_f32_e32 v242, v242, v243
	v_add_f32_e32 v244, v244, v245
	v_add_f32_e32 v216, v216, v217
	v_add_f32_e32 v218, v218, v219
	v_add_f32_e32 v242, v242, v244
	v_add_f32_e32 v216, v216, v218
	v_add_f32_e32 v227, v242, v216
	v_cvt_pk_bf16_f32 v230, v124, v125
	v_cvt_pk_bf16_f32 v231, v126, v127
	v_cvt_pk_bf16_f32 v232, v120, v121
	v_cvt_pk_bf16_f32 v233, v122, v123
	global_store_dwordx4 v223, v[230:233], s[100:101]
	v_lshlrev_b32_e32 v220, 16, v154
	v_and_b32_e32 v221, 0xffff0000, v154
	v_pk_add_f32 v[116:117], v[116:117], v[220:221]
	v_lshlrev_b32_e32 v220, 16, v155
	v_and_b32_e32 v221, 0xffff0000, v155
	v_pk_add_f32 v[118:119], v[118:119], v[220:221]
	v_lshlrev_b32_e32 v220, 16, v156
	v_and_b32_e32 v221, 0xffff0000, v156
	v_pk_add_f32 v[112:113], v[112:113], v[220:221]
	v_lshlrev_b32_e32 v220, 16, v157
	v_and_b32_e32 v221, 0xffff0000, v157
	v_pk_add_f32 v[114:115], v[114:115], v[220:221]
	v_pk_mul_f32 v[242:243], v[116:117], v[116:117]
	v_pk_mul_f32 v[244:245], v[118:119], v[118:119]
	v_pk_mul_f32 v[216:217], v[112:113], v[112:113]
	v_pk_mul_f32 v[218:219], v[114:115], v[114:115]
	v_add_f32_e32 v242, v242, v243
	v_add_f32_e32 v244, v244, v245
	v_add_f32_e32 v216, v216, v217
	v_add_f32_e32 v218, v218, v219
	v_add_f32_e32 v242, v242, v244
	v_add_f32_e32 v216, v216, v218
	v_add_f32_e32 v228, v242, v216
	v_cvt_pk_bf16_f32 v234, v116, v117
	v_cvt_pk_bf16_f32 v235, v118, v119
	v_cvt_pk_bf16_f32 v236, v112, v113
	v_cvt_pk_bf16_f32 v237, v114, v115
	global_store_dwordx4 v223, v[234:237], s[100:101] offset:256
	v_add_f32_e32 v227, v227, v228
	ds_bpermute_b32 v228, v225, v227
	s_waitcnt lgkmcnt(0)
	v_add_f32_e32 v227, v227, v228
	ds_bpermute_b32 v228, v226, v227
	s_waitcnt lgkmcnt(0)
	v_add_f32_e32 v227, v227, v228
	s_and_saveexec_b64 s[22:23], vcc
	global_store_dword v224, v227, s[24:25]
	s_or_b64 exec, exec, s[22:23]
	s_add_u32 s100, s100, 0x8000
	s_addc_u32 s101, s101, 0
	s_add_u32 s24, s24, 0x400
	s_addc_u32 s25, s25, 0
	v_lshlrev_b32_e32 v220, 16, v158
	v_and_b32_e32 v221, 0xffff0000, v158
	v_pk_add_f32 v[108:109], v[108:109], v[220:221]
	v_lshlrev_b32_e32 v220, 16, v159
	v_and_b32_e32 v221, 0xffff0000, v159
	v_pk_add_f32 v[110:111], v[110:111], v[220:221]
	v_lshlrev_b32_e32 v220, 16, v160
	v_and_b32_e32 v221, 0xffff0000, v160
	v_pk_add_f32 v[104:105], v[104:105], v[220:221]
	v_lshlrev_b32_e32 v220, 16, v161
	v_and_b32_e32 v221, 0xffff0000, v161
	v_pk_add_f32 v[106:107], v[106:107], v[220:221]
	v_pk_mul_f32 v[242:243], v[108:109], v[108:109]
	v_pk_mul_f32 v[244:245], v[110:111], v[110:111]
	v_pk_mul_f32 v[216:217], v[104:105], v[104:105]
	v_pk_mul_f32 v[218:219], v[106:107], v[106:107]
	v_add_f32_e32 v242, v242, v243
	v_add_f32_e32 v244, v244, v245
	v_add_f32_e32 v216, v216, v217
	v_add_f32_e32 v218, v218, v219
	v_add_f32_e32 v242, v242, v244
	v_add_f32_e32 v216, v216, v218
	v_add_f32_e32 v227, v242, v216
	v_cvt_pk_bf16_f32 v230, v108, v109
	v_cvt_pk_bf16_f32 v231, v110, v111
	v_cvt_pk_bf16_f32 v232, v104, v105
	v_cvt_pk_bf16_f32 v233, v106, v107
	global_store_dwordx4 v223, v[230:233], s[100:101]
	v_lshlrev_b32_e32 v220, 16, v162
	v_and_b32_e32 v221, 0xffff0000, v162
	v_pk_add_f32 v[100:101], v[100:101], v[220:221]
	v_lshlrev_b32_e32 v220, 16, v163
	v_and_b32_e32 v221, 0xffff0000, v163
	v_pk_add_f32 v[102:103], v[102:103], v[220:221]
	v_lshlrev_b32_e32 v220, 16, v164
	v_and_b32_e32 v221, 0xffff0000, v164
	v_pk_add_f32 v[96:97], v[96:97], v[220:221]
	v_lshlrev_b32_e32 v220, 16, v165
	v_and_b32_e32 v221, 0xffff0000, v165
	v_pk_add_f32 v[98:99], v[98:99], v[220:221]
	v_pk_mul_f32 v[242:243], v[100:101], v[100:101]
	v_pk_mul_f32 v[244:245], v[102:103], v[102:103]
	v_pk_mul_f32 v[216:217], v[96:97], v[96:97]
	v_pk_mul_f32 v[218:219], v[98:99], v[98:99]
	v_add_f32_e32 v242, v242, v243
	v_add_f32_e32 v244, v244, v245
	v_add_f32_e32 v216, v216, v217
	v_add_f32_e32 v218, v218, v219
	v_add_f32_e32 v242, v242, v244
	v_add_f32_e32 v216, v216, v218
	v_add_f32_e32 v228, v242, v216
	v_cvt_pk_bf16_f32 v234, v100, v101
	v_cvt_pk_bf16_f32 v235, v102, v103
	v_cvt_pk_bf16_f32 v236, v96, v97
	v_cvt_pk_bf16_f32 v237, v98, v99
	global_store_dwordx4 v223, v[234:237], s[100:101] offset:256
	v_add_f32_e32 v227, v227, v228
	ds_bpermute_b32 v228, v225, v227
	s_waitcnt lgkmcnt(0)
; __device__ __forceinline__ u32x4 pack8(f32x4 a, f32x4 b) { u32x4 w; w.x = cvt_pk(a[0], a[1]); w.y = cvt_pk(a[2], a[3]); w.z = cvt_pk(b[0], b[1]); w.w = cvt_pk(b[2], b[3]); return w; }
;     __device__ __forceinline__ void operator()(EPI_ARGS) const {
;     ...
;             for (int m = 0; m < 4; ++m) { const int row = row0 + ai * 128 + m * 16; const size_t ro = (size_t)row * DM + colt; float s = 0.f;
; #pragma unroll
;                 for (int bj = 0; bj < 2; ++bj) { const size_t o = ro + bj * 128;
;                     f32x4 v0 = acc[ai][bj][m][0], v1 = acc[ai][bj][m][1];
;                     if (IN_BF16) { const u32x4 t = *(const u32x4*)((const bf16_t*)xin + o);
;                         v0[0] += bflo(t.x); v0[1] += bfhi(t.x); v0[2] += bflo(t.y); v0[3] += bfhi(t.y); v1[0] += bflo(t.z); v1[1] += bfhi(t.z); v1[2] += bflo(t.w); v1[3] += bfhi(t.w);
;                     } else { v0 = v0 + *(const f32x4*)((const float*)xin + o); v1 = v1 + *(const f32x4*)((const float*)xin + o + 4); }
;                     *(u32x4*)(xb + o) = pack8(v0, v1);
;                     s += ((v0[0] * v0[0] + v0[1] * v0[1]) + (v0[2] * v0[2] + v0[3] * v0[3])) + ((v1[0] * v1[0] + v1[1] * v1[1]) + (v1[2] * v1[2] + v1[3] * v1[3])); }
;                 s += __shfl_xor(s, 16); s += __shfl_xor(s, 32);
;                 if (fq == 0) ss[(size_t)row * 16 + u.pn * 4 + wc] = s; }
	v_add_f32_e32 v227, v227, v228
	ds_bpermute_b32 v228, v226, v227
	s_waitcnt lgkmcnt(0)
	v_add_f32_e32 v227, v227, v228
	s_and_saveexec_b64 s[22:23], vcc
	global_store_dword v224, v227, s[24:25]
	s_or_b64 exec, exec, s[22:23]
	s_add_u32 s100, s100, 0x8000
	s_addc_u32 s101, s101, 0
	s_add_u32 s24, s24, 0x400
	s_addc_u32 s25, s25, 0
	v_lshlrev_b32_e32 v220, 16, v166
	v_and_b32_e32 v221, 0xffff0000, v166
	v_pk_add_f32 v[92:93], v[92:93], v[220:221]
	v_lshlrev_b32_e32 v220, 16, v167
	v_and_b32_e32 v221, 0xffff0000, v167
	v_pk_add_f32 v[94:95], v[94:95], v[220:221]
	v_lshlrev_b32_e32 v220, 16, v168
	v_and_b32_e32 v221, 0xffff0000, v168
	v_pk_add_f32 v[88:89], v[88:89], v[220:221]
	v_lshlrev_b32_e32 v220, 16, v169
	v_and_b32_e32 v221, 0xffff0000, v169
	v_pk_add_f32 v[90:91], v[90:91], v[220:221]
	v_pk_mul_f32 v[242:243], v[92:93], v[92:93]
	v_pk_mul_f32 v[244:245], v[94:95], v[94:95]
	v_pk_mul_f32 v[216:217], v[88:89], v[88:89]
	v_pk_mul_f32 v[218:219], v[90:91], v[90:91]
	v_add_f32_e32 v242, v242, v243
	v_add_f32_e32 v244, v244, v245
	v_add_f32_e32 v216, v216, v217
	v_add_f32_e32 v218, v218, v219
	v_add_f32_e32 v242, v242, v244
	v_add_f32_e32 v216, v216, v218
	v_add_f32_e32 v227, v242, v216
	v_cvt_pk_bf16_f32 v230, v92, v93
	v_cvt_pk_bf16_f32 v231, v94, v95
	v_cvt_pk_bf16_f32 v232, v88, v89
	v_cvt_pk_bf16_f32 v233, v90, v91
	global_store_dwordx4 v223, v[230:233], s[100:101]
	v_lshlrev_b32_e32 v220, 16, v170
	v_and_b32_e32 v221, 0xffff0000, v170
	v_pk_add_f32 v[84:85], v[84:85], v[220:221]
	v_lshlrev_b32_e32 v220, 16, v171
	v_and_b32_e32 v221, 0xffff0000, v171
	v_pk_add_f32 v[86:87], v[86:87], v[220:221]
	v_lshlrev_b32_e32 v220, 16, v172
	v_and_b32_e32 v221, 0xffff0000, v172
	v_pk_add_f32 v[80:81], v[80:81], v[220:221]
	v_lshlrev_b32_e32 v220, 16, v173
	v_and_b32_e32 v221, 0xffff0000, v173
	v_pk_add_f32 v[82:83], v[82:83], v[220:221]
	v_pk_mul_f32 v[242:243], v[84:85], v[84:85]
	v_pk_mul_f32 v[244:245], v[86:87], v[86:87]
	v_pk_mul_f32 v[216:217], v[80:81], v[80:81]
	v_pk_mul_f32 v[218:219], v[82:83], v[82:83]
	v_add_f32_e32 v242, v242, v243
	v_add_f32_e32 v244, v244, v245
	v_add_f32_e32 v216, v216, v217
	v_add_f32_e32 v218, v218, v219
	v_add_f32_e32 v242, v242, v244
	v_add_f32_e32 v216, v216, v218
	v_add_f32_e32 v228, v242, v216
	v_cvt_pk_bf16_f32 v234, v84, v85
	v_cvt_pk_bf16_f32 v235, v86, v87
	v_cvt_pk_bf16_f32 v236, v80, v81
	v_cvt_pk_bf16_f32 v237, v82, v83
	global_store_dwordx4 v223, v[234:237], s[100:101] offset:256
	v_add_f32_e32 v227, v227, v228
	ds_bpermute_b32 v228, v225, v227
	s_waitcnt lgkmcnt(0)
	v_add_f32_e32 v227, v227, v228
	ds_bpermute_b32 v228, v226, v227
	s_waitcnt lgkmcnt(0)
	v_add_f32_e32 v227, v227, v228
	s_and_saveexec_b64 s[22:23], vcc
	global_store_dword v224, v227, s[24:25]
	s_or_b64 exec, exec, s[22:23]
	s_add_u32 s100, s100, 0x8000
	s_addc_u32 s101, s101, 0
	s_add_u32 s24, s24, 0x400
	s_addc_u32 s25, s25, 0
	v_lshlrev_b32_e32 v220, 16, v174
	v_and_b32_e32 v221, 0xffff0000, v174
	v_pk_add_f32 v[76:77], v[76:77], v[220:221]
	v_lshlrev_b32_e32 v220, 16, v175
	v_and_b32_e32 v221, 0xffff0000, v175
	v_pk_add_f32 v[78:79], v[78:79], v[220:221]
	v_lshlrev_b32_e32 v220, 16, v176
	v_and_b32_e32 v221, 0xffff0000, v176
	v_pk_add_f32 v[72:73], v[72:73], v[220:221]
	v_lshlrev_b32_e32 v220, 16, v177
	v_and_b32_e32 v221, 0xffff0000, v177
	v_pk_add_f32 v[74:75], v[74:75], v[220:221]
	v_pk_mul_f32 v[242:243], v[76:77], v[76:77]
	v_pk_mul_f32 v[244:245], v[78:79], v[78:79]
	v_pk_mul_f32 v[216:217], v[72:73], v[72:73]
	v_pk_mul_f32 v[218:219], v[74:75], v[74:75]
	v_add_f32_e32 v242, v242, v243
	v_add_f32_e32 v244, v244, v245
	v_add_f32_e32 v216, v216, v217
	v_add_f32_e32 v218, v218, v219
	v_add_f32_e32 v242, v242, v244
	v_add_f32_e32 v216, v216, v218
	v_add_f32_e32 v227, v242, v216
	v_cvt_pk_bf16_f32 v230, v76, v77
	v_cvt_pk_bf16_f32 v231, v78, v79
	v_cvt_pk_bf16_f32 v232, v72, v73
	v_cvt_pk_bf16_f32 v233, v74, v75
	global_store_dwordx4 v223, v[230:233], s[100:101]
	v_lshlrev_b32_e32 v220, 16, v178
	v_and_b32_e32 v221, 0xffff0000, v178
	v_pk_add_f32 v[68:69], v[68:69], v[220:221]
	v_lshlrev_b32_e32 v220, 16, v179
	v_and_b32_e32 v221, 0xffff0000, v179
	v_pk_add_f32 v[70:71], v[70:71], v[220:221]
	v_lshlrev_b32_e32 v220, 16, v180
	v_and_b32_e32 v221, 0xffff0000, v180
	v_pk_add_f32 v[64:65], v[64:65], v[220:221]
	v_lshlrev_b32_e32 v220, 16, v181
	v_and_b32_e32 v221, 0xffff0000, v181
	v_pk_add_f32 v[66:67], v[66:67], v[220:221]
	v_pk_mul_f32 v[242:243], v[68:69], v[68:69]
	v_pk_mul_f32 v[244:245], v[70:71], v[70:71]
	v_pk_mul_f32 v[216:217], v[64:65], v[64:65]
	v_pk_mul_f32 v[218:219], v[66:67], v[66:67]
	v_add_f32_e32 v242, v242, v243
	v_add_f32_e32 v244, v244, v245
	v_add_f32_e32 v216, v216, v217
	v_add_f32_e32 v218, v218, v219
	v_add_f32_e32 v242, v242, v244
	v_add_f32_e32 v216, v216, v218
	v_add_f32_e32 v228, v242, v216
	v_cvt_pk_bf16_f32 v234, v68, v69
	v_cvt_pk_bf16_f32 v235, v70, v71
	v_cvt_pk_bf16_f32 v236, v64, v65
	v_cvt_pk_bf16_f32 v237, v66, v67
	global_store_dwordx4 v223, v[234:237], s[100:101] offset:256
	v_add_f32_e32 v227, v227, v228
	ds_bpermute_b32 v228, v225, v227
	s_waitcnt lgkmcnt(0)
	v_add_f32_e32 v227, v227, v228
	ds_bpermute_b32 v228, v226, v227
	s_waitcnt lgkmcnt(0)
; __device__ __forceinline__ u32x4 pack8(f32x4 a, f32x4 b) { u32x4 w; w.x = cvt_pk(a[0], a[1]); w.y = cvt_pk(a[2], a[3]); w.z = cvt_pk(b[0], b[1]); w.w = cvt_pk(b[2], b[3]); return w; }
;     __device__ __forceinline__ void operator()(EPI_ARGS) const {
;     ...
;             for (int m = 0; m < 4; ++m) { const int row = row0 + ai * 128 + m * 16; const size_t ro = (size_t)row * DM + colt; float s = 0.f;
; #pragma unroll
;                 for (int bj = 0; bj < 2; ++bj) { const size_t o = ro + bj * 128;
;                     f32x4 v0 = acc[ai][bj][m][0], v1 = acc[ai][bj][m][1];
;                     if (IN_BF16) { const u32x4 t = *(const u32x4*)((const bf16_t*)xin + o);
;                         v0[0] += bflo(t.x); v0[1] += bfhi(t.x); v0[2] += bflo(t.y); v0[3] += bfhi(t.y); v1[0] += bflo(t.z); v1[1] += bfhi(t.z); v1[2] += bflo(t.w); v1[3] += bfhi(t.w);
;                     } else { v0 = v0 + *(const f32x4*)((const float*)xin + o); v1 = v1 + *(const f32x4*)((const float*)xin + o + 4); }
;                     *(u32x4*)(xb + o) = pack8(v0, v1);
;                     s += ((v0[0] * v0[0] + v0[1] * v0[1]) + (v0[2] * v0[2] + v0[3] * v0[3])) + ((v1[0] * v1[0] + v1[1] * v1[1]) + (v1[2] * v1[2] + v1[3] * v1[3])); }
;                 s += __shfl_xor(s, 16); s += __shfl_xor(s, 32);
;                 if (fq == 0) ss[(size_t)row * 16 + u.pn * 4 + wc] = s; }
	v_add_f32_e32 v227, v227, v228
	s_and_saveexec_b64 s[22:23], vcc
	global_store_dword v224, v227, s[24:25]
	s_or_b64 exec, exec, s[22:23]
	s_add_u32 s100, s100, 0x28000
	s_addc_u32 s101, s101, 0
	s_add_u32 s24, s24, 0x1400
	s_addc_u32 s25, s25, 0
	v_lshlrev_b32_e32 v220, 16, v186
	v_and_b32_e32 v221, 0xffff0000, v186
	v_pk_add_f32 v[60:61], v[60:61], v[220:221]
	v_lshlrev_b32_e32 v220, 16, v187
	v_and_b32_e32 v221, 0xffff0000, v187
	v_pk_add_f32 v[62:63], v[62:63], v[220:221]
	v_lshlrev_b32_e32 v220, 16, v188
	v_and_b32_e32 v221, 0xffff0000, v188
	v_pk_add_f32 v[56:57], v[56:57], v[220:221]
	v_lshlrev_b32_e32 v220, 16, v189
	v_and_b32_e32 v221, 0xffff0000, v189
	v_pk_add_f32 v[58:59], v[58:59], v[220:221]
	v_pk_mul_f32 v[242:243], v[60:61], v[60:61]
	v_pk_mul_f32 v[244:245], v[62:63], v[62:63]
	v_pk_mul_f32 v[216:217], v[56:57], v[56:57]
	v_pk_mul_f32 v[218:219], v[58:59], v[58:59]
	v_add_f32_e32 v242, v242, v243
	v_add_f32_e32 v244, v244, v245
	v_add_f32_e32 v216, v216, v217
	v_add_f32_e32 v218, v218, v219
	v_add_f32_e32 v242, v242, v244
	v_add_f32_e32 v216, v216, v218
	v_add_f32_e32 v227, v242, v216
	v_cvt_pk_bf16_f32 v230, v60, v61
	v_cvt_pk_bf16_f32 v231, v62, v63
	v_cvt_pk_bf16_f32 v232, v56, v57
	v_cvt_pk_bf16_f32 v233, v58, v59
	global_store_dwordx4 v223, v[230:233], s[100:101]
	v_lshlrev_b32_e32 v220, 16, v190
	v_and_b32_e32 v221, 0xffff0000, v190
	v_pk_add_f32 v[52:53], v[52:53], v[220:221]
	v_lshlrev_b32_e32 v220, 16, v191
	v_and_b32_e32 v221, 0xffff0000, v191
	v_pk_add_f32 v[54:55], v[54:55], v[220:221]
	v_lshlrev_b32_e32 v220, 16, v192
	v_and_b32_e32 v221, 0xffff0000, v192
	v_pk_add_f32 v[48:49], v[48:49], v[220:221]
	v_lshlrev_b32_e32 v220, 16, v193
	v_and_b32_e32 v221, 0xffff0000, v193
	v_pk_add_f32 v[50:51], v[50:51], v[220:221]
	v_pk_mul_f32 v[242:243], v[52:53], v[52:53]
	v_pk_mul_f32 v[244:245], v[54:55], v[54:55]
	v_pk_mul_f32 v[216:217], v[48:49], v[48:49]
	v_pk_mul_f32 v[218:219], v[50:51], v[50:51]
	v_add_f32_e32 v242, v242, v243
	v_add_f32_e32 v244, v244, v245
	v_add_f32_e32 v216, v216, v217
	v_add_f32_e32 v218, v218, v219
	v_add_f32_e32 v242, v242, v244
	v_add_f32_e32 v216, v216, v218
	v_add_f32_e32 v228, v242, v216
	v_cvt_pk_bf16_f32 v234, v52, v53
	v_cvt_pk_bf16_f32 v235, v54, v55
	v_cvt_pk_bf16_f32 v236, v48, v49
	v_cvt_pk_bf16_f32 v237, v50, v51
	global_store_dwordx4 v223, v[234:237], s[100:101] offset:256
	v_add_f32_e32 v227, v227, v228
	ds_bpermute_b32 v228, v225, v227
	s_waitcnt lgkmcnt(0)
	v_add_f32_e32 v227, v227, v228
	ds_bpermute_b32 v228, v226, v227
	s_waitcnt lgkmcnt(0)
	v_add_f32_e32 v227, v227, v228
	s_and_saveexec_b64 s[22:23], vcc
	global_store_dword v224, v227, s[24:25]
	s_or_b64 exec, exec, s[22:23]
	s_add_u32 s100, s100, 0x8000
	s_addc_u32 s101, s101, 0
	s_add_u32 s24, s24, 0x400
	s_addc_u32 s25, s25, 0
	v_lshlrev_b32_e32 v220, 16, v194
	v_and_b32_e32 v221, 0xffff0000, v194
	v_pk_add_f32 v[44:45], v[44:45], v[220:221]
	v_lshlrev_b32_e32 v220, 16, v195
	v_and_b32_e32 v221, 0xffff0000, v195
	v_pk_add_f32 v[46:47], v[46:47], v[220:221]
	v_lshlrev_b32_e32 v220, 16, v196
	v_and_b32_e32 v221, 0xffff0000, v196
	v_pk_add_f32 v[40:41], v[40:41], v[220:221]
	v_lshlrev_b32_e32 v220, 16, v197
	v_and_b32_e32 v221, 0xffff0000, v197
	v_pk_add_f32 v[42:43], v[42:43], v[220:221]
	v_pk_mul_f32 v[242:243], v[44:45], v[44:45]
	v_pk_mul_f32 v[244:245], v[46:47], v[46:47]
	v_pk_mul_f32 v[216:217], v[40:41], v[40:41]
	v_pk_mul_f32 v[218:219], v[42:43], v[42:43]
	v_add_f32_e32 v242, v242, v243
	v_add_f32_e32 v244, v244, v245
	v_add_f32_e32 v216, v216, v217
	v_add_f32_e32 v218, v218, v219
	v_add_f32_e32 v242, v242, v244
	v_add_f32_e32 v216, v216, v218
	v_add_f32_e32 v227, v242, v216
	v_cvt_pk_bf16_f32 v230, v44, v45
	v_cvt_pk_bf16_f32 v231, v46, v47
	v_cvt_pk_bf16_f32 v232, v40, v41
	v_cvt_pk_bf16_f32 v233, v42, v43
	global_store_dwordx4 v223, v[230:233], s[100:101]
	v_lshlrev_b32_e32 v220, 16, v198
	v_and_b32_e32 v221, 0xffff0000, v198
	v_pk_add_f32 v[36:37], v[36:37], v[220:221]
	v_lshlrev_b32_e32 v220, 16, v199
	v_and_b32_e32 v221, 0xffff0000, v199
	v_pk_add_f32 v[38:39], v[38:39], v[220:221]
	v_lshlrev_b32_e32 v220, 16, v200
	v_and_b32_e32 v221, 0xffff0000, v200
	v_pk_add_f32 v[32:33], v[32:33], v[220:221]
	v_lshlrev_b32_e32 v220, 16, v201
	v_and_b32_e32 v221, 0xffff0000, v201
	v_pk_add_f32 v[34:35], v[34:35], v[220:221]
	v_pk_mul_f32 v[242:243], v[36:37], v[36:37]
	v_pk_mul_f32 v[244:245], v[38:39], v[38:39]
	v_pk_mul_f32 v[216:217], v[32:33], v[32:33]
	v_pk_mul_f32 v[218:219], v[34:35], v[34:35]
	v_add_f32_e32 v242, v242, v243
	v_add_f32_e32 v244, v244, v245
	v_add_f32_e32 v216, v216, v217
	v_add_f32_e32 v218, v218, v219
	v_add_f32_e32 v242, v242, v244
	v_add_f32_e32 v216, v216, v218
	v_add_f32_e32 v228, v242, v216
	v_cvt_pk_bf16_f32 v234, v36, v37
	v_cvt_pk_bf16_f32 v235, v38, v39
	v_cvt_pk_bf16_f32 v236, v32, v33
	v_cvt_pk_bf16_f32 v237, v34, v35
	global_store_dwordx4 v223, v[234:237], s[100:101] offset:256
	v_add_f32_e32 v227, v227, v228
	ds_bpermute_b32 v228, v225, v227
	s_waitcnt lgkmcnt(0)
	v_add_f32_e32 v227, v227, v228
	ds_bpermute_b32 v228, v226, v227
	s_waitcnt lgkmcnt(0)
; __device__ __forceinline__ u32x4 pack8(f32x4 a, f32x4 b) { u32x4 w; w.x = cvt_pk(a[0], a[1]); w.y = cvt_pk(a[2], a[3]); w.z = cvt_pk(b[0], b[1]); w.w = cvt_pk(b[2], b[3]); return w; }
;     __device__ __forceinline__ void operator()(EPI_ARGS) const {
;     ...
;             for (int m = 0; m < 4; ++m) { const int row = row0 + ai * 128 + m * 16; const size_t ro = (size_t)row * DM + colt; float s = 0.f;
; #pragma unroll
;                 for (int bj = 0; bj < 2; ++bj) { const size_t o = ro + bj * 128;
;                     f32x4 v0 = acc[ai][bj][m][0], v1 = acc[ai][bj][m][1];
;                     if (IN_BF16) { const u32x4 t = *(const u32x4*)((const bf16_t*)xin + o);
;                         v0[0] += bflo(t.x); v0[1] += bfhi(t.x); v0[2] += bflo(t.y); v0[3] += bfhi(t.y); v1[0] += bflo(t.z); v1[1] += bfhi(t.z); v1[2] += bflo(t.w); v1[3] += bfhi(t.w);
;                     } else { v0 = v0 + *(const f32x4*)((const float*)xin + o); v1 = v1 + *(const f32x4*)((const float*)xin + o + 4); }
;                     *(u32x4*)(xb + o) = pack8(v0, v1);
;                     s += ((v0[0] * v0[0] + v0[1] * v0[1]) + (v0[2] * v0[2] + v0[3] * v0[3])) + ((v1[0] * v1[0] + v1[1] * v1[1]) + (v1[2] * v1[2] + v1[3] * v1[3])); }
;                 s += __shfl_xor(s, 16); s += __shfl_xor(s, 32);
;                 if (fq == 0) ss[(size_t)row * 16 + u.pn * 4 + wc] = s; }
	v_add_f32_e32 v227, v227, v228
	s_and_saveexec_b64 s[22:23], vcc
	global_store_dword v224, v227, s[24:25]
	s_or_b64 exec, exec, s[22:23]
	s_add_u32 s100, s100, 0x8000
	s_addc_u32 s101, s101, 0
	s_add_u32 s24, s24, 0x400
	s_addc_u32 s25, s25, 0
	v_lshlrev_b32_e32 v220, 16, v202
	v_and_b32_e32 v221, 0xffff0000, v202
	v_pk_add_f32 v[28:29], v[28:29], v[220:221]
	v_lshlrev_b32_e32 v220, 16, v203
	v_and_b32_e32 v221, 0xffff0000, v203
	v_pk_add_f32 v[30:31], v[30:31], v[220:221]
	v_lshlrev_b32_e32 v220, 16, v204
	v_and_b32_e32 v221, 0xffff0000, v204
	v_pk_add_f32 v[24:25], v[24:25], v[220:221]
	v_lshlrev_b32_e32 v220, 16, v205
	v_and_b32_e32 v221, 0xffff0000, v205
	v_pk_add_f32 v[26:27], v[26:27], v[220:221]
	v_pk_mul_f32 v[242:243], v[28:29], v[28:29]
	v_pk_mul_f32 v[244:245], v[30:31], v[30:31]
	v_pk_mul_f32 v[216:217], v[24:25], v[24:25]
	v_pk_mul_f32 v[218:219], v[26:27], v[26:27]
	v_add_f32_e32 v242, v242, v243
	v_add_f32_e32 v244, v244, v245
	v_add_f32_e32 v216, v216, v217
	v_add_f32_e32 v218, v218, v219
	v_add_f32_e32 v242, v242, v244
	v_add_f32_e32 v216, v216, v218
	v_add_f32_e32 v227, v242, v216
	v_cvt_pk_bf16_f32 v230, v28, v29
	v_cvt_pk_bf16_f32 v231, v30, v31
	v_cvt_pk_bf16_f32 v232, v24, v25
	v_cvt_pk_bf16_f32 v233, v26, v27
	global_store_dwordx4 v223, v[230:233], s[100:101]
	v_lshlrev_b32_e32 v220, 16, v206
	v_and_b32_e32 v221, 0xffff0000, v206
	v_pk_add_f32 v[20:21], v[20:21], v[220:221]
	v_lshlrev_b32_e32 v220, 16, v207
	v_and_b32_e32 v221, 0xffff0000, v207
	v_pk_add_f32 v[22:23], v[22:23], v[220:221]
	v_lshlrev_b32_e32 v220, 16, v208
	v_and_b32_e32 v221, 0xffff0000, v208
	v_pk_add_f32 v[16:17], v[16:17], v[220:221]
	v_lshlrev_b32_e32 v220, 16, v209
	v_and_b32_e32 v221, 0xffff0000, v209
	v_pk_add_f32 v[18:19], v[18:19], v[220:221]
	v_pk_mul_f32 v[242:243], v[20:21], v[20:21]
	v_pk_mul_f32 v[244:245], v[22:23], v[22:23]
	v_pk_mul_f32 v[216:217], v[16:17], v[16:17]
	v_pk_mul_f32 v[218:219], v[18:19], v[18:19]
	v_add_f32_e32 v242, v242, v243
	v_add_f32_e32 v244, v244, v245
	v_add_f32_e32 v216, v216, v217
	v_add_f32_e32 v218, v218, v219
	v_add_f32_e32 v242, v242, v244
	v_add_f32_e32 v216, v216, v218
	v_add_f32_e32 v228, v242, v216
	v_cvt_pk_bf16_f32 v234, v20, v21
	v_cvt_pk_bf16_f32 v235, v22, v23
	v_cvt_pk_bf16_f32 v236, v16, v17
	v_cvt_pk_bf16_f32 v237, v18, v19
	global_store_dwordx4 v223, v[234:237], s[100:101] offset:256
	v_add_f32_e32 v227, v227, v228
	ds_bpermute_b32 v228, v225, v227
	s_waitcnt lgkmcnt(0)
	v_add_f32_e32 v227, v227, v228
	ds_bpermute_b32 v228, v226, v227
	s_waitcnt lgkmcnt(0)
	v_add_f32_e32 v227, v227, v228
	s_and_saveexec_b64 s[22:23], vcc
	global_store_dword v224, v227, s[24:25]
	s_or_b64 exec, exec, s[22:23]
	s_add_u32 s100, s100, 0x8000
	s_addc_u32 s101, s101, 0
	s_add_u32 s24, s24, 0x400
	s_addc_u32 s25, s25, 0
	v_lshlrev_b32_e32 v220, 16, v210
	v_and_b32_e32 v221, 0xffff0000, v210
	v_pk_add_f32 v[12:13], v[12:13], v[220:221]
	v_lshlrev_b32_e32 v220, 16, v211
	v_and_b32_e32 v221, 0xffff0000, v211
	v_pk_add_f32 v[14:15], v[14:15], v[220:221]
	v_lshlrev_b32_e32 v220, 16, v212
	v_and_b32_e32 v221, 0xffff0000, v212
	v_pk_add_f32 v[8:9], v[8:9], v[220:221]
	v_lshlrev_b32_e32 v220, 16, v213
	v_and_b32_e32 v221, 0xffff0000, v213
	v_pk_add_f32 v[10:11], v[10:11], v[220:221]
	v_pk_mul_f32 v[242:243], v[12:13], v[12:13]
	v_pk_mul_f32 v[244:245], v[14:15], v[14:15]
	v_pk_mul_f32 v[216:217], v[8:9], v[8:9]
	v_pk_mul_f32 v[218:219], v[10:11], v[10:11]
	v_add_f32_e32 v242, v242, v243
	v_add_f32_e32 v244, v244, v245
	v_add_f32_e32 v216, v216, v217
	v_add_f32_e32 v218, v218, v219
	v_add_f32_e32 v242, v242, v244
	v_add_f32_e32 v216, v216, v218
	v_add_f32_e32 v227, v242, v216
	v_cvt_pk_bf16_f32 v230, v12, v13
	v_cvt_pk_bf16_f32 v231, v14, v15
	v_cvt_pk_bf16_f32 v232, v8, v9
	v_cvt_pk_bf16_f32 v233, v10, v11
	global_store_dwordx4 v223, v[230:233], s[100:101]
	v_lshlrev_b32_e32 v220, 16, v238
	v_and_b32_e32 v221, 0xffff0000, v238
	v_pk_add_f32 v[4:5], v[4:5], v[220:221]
	v_lshlrev_b32_e32 v220, 16, v239
	v_and_b32_e32 v221, 0xffff0000, v239
	v_pk_add_f32 v[6:7], v[6:7], v[220:221]
	v_lshlrev_b32_e32 v220, 16, v240
	v_and_b32_e32 v221, 0xffff0000, v240
	v_pk_add_f32 v[0:1], v[0:1], v[220:221]
	v_lshlrev_b32_e32 v220, 16, v241
	v_and_b32_e32 v221, 0xffff0000, v241
	v_pk_add_f32 v[2:3], v[2:3], v[220:221]
	v_pk_mul_f32 v[242:243], v[4:5], v[4:5]
	v_pk_mul_f32 v[244:245], v[6:7], v[6:7]
	v_pk_mul_f32 v[216:217], v[0:1], v[0:1]
	v_pk_mul_f32 v[218:219], v[2:3], v[2:3]
	v_add_f32_e32 v242, v242, v243
	v_add_f32_e32 v244, v244, v245
	v_add_f32_e32 v216, v216, v217
	v_add_f32_e32 v218, v218, v219
	v_add_f32_e32 v242, v242, v244
	v_add_f32_e32 v216, v216, v218
	v_add_f32_e32 v228, v242, v216
	v_cvt_pk_bf16_f32 v234, v4, v5
	v_cvt_pk_bf16_f32 v235, v6, v7
	v_cvt_pk_bf16_f32 v236, v0, v1
	v_cvt_pk_bf16_f32 v237, v2, v3
	global_store_dwordx4 v223, v[234:237], s[100:101] offset:256
	v_add_f32_e32 v227, v227, v228
	ds_bpermute_b32 v228, v225, v227
	s_waitcnt lgkmcnt(0)
	v_add_f32_e32 v227, v227, v228
	ds_bpermute_b32 v228, v226, v227
	s_waitcnt lgkmcnt(0)
	v_add_f32_e32 v227, v227, v228
	s_and_saveexec_b64 s[22:23], vcc
	global_store_dword v224, v227, s[24:25]
	s_or_b64 exec, exec, s[22:23]
	s_add_u32 s100, s100, 0x28000
	s_addc_u32 s101, s101, 0
	s_add_u32 s24, s24, 0x1400
	s_addc_u32 s25, s25, 0
	s_andn2_b64 vcc, exec, s[16:17]
	s_mov_b64 s[16:17], -1
	s_cbranch_vccnz .LBB0_952
	s_andn2_b64 vcc, exec, s[6:7]
	s_cbranch_vccnz .LBB0_951
	s_barrier
	s_branch .LBB0_951
